# same-layer windows, B window enlarged to 2 iterations (A=2,P=3,B=2)
# speedup vs baseline: 1.0103x; 1.0014x over previous
; #define LAS __attribute__((address_space(3)))
; __device__ __forceinline__ void convert_layer_static(const PT& a, LAS unsigned char* lds, int l, int gw, int NGW, int wave, int lane, int r_end = IT_LAYER) {
;     for (int r = 2 * gw; r < r_end; r += 2 * NGW) cv_pair(a, lds, l, r, wave, lane);
; }
; __device__ __forceinline__ void prologue_a(const PT& a, LAS unsigned char* lds) {
;     ...
;     convert_layer_static(a, lds, 0, gw, NGW, wave, lane);
;     for (int cl_ = 1; cl_ < DEPTH; ++cl_) convert_layer_static(a, lds, cl_, gw, NGW, wave, lane, CV_PRO_ITEMS);
.LBB0_110:
	s_or_b64 exec, exec, s[12:13]
	v_lshl_add_u32 v2, v74, 2, v115
	v_add_u32_e32 v3, v115, v113
	s_mov_b32 s13, 0
	v_lshl_add_u32 v113, v67, 2, v3
	v_lshl_add_u32 v115, v69, 2, v3
	v_lshl_add_u32 v117, v97, 2, v3
	v_lshl_add_u32 v119, v99, 2, v3
	s_mov_b32 s18, 1
	s_lshl_b32 s42, s17, 5
	s_movk_i32 s43, 0x393f
	s_movk_i32 s44, 0x453f
	s_movk_i32 s45, 0x4d3f
	s_movk_i32 s46, 0x793f
	s_movk_i32 s47, 0x15ff
	s_movk_i32 s48, 0xba3
	s_movk_i32 s49, 0x1600
	s_movk_i32 s50, 0x3ff
	v_mov_b32_e32 v79, 0
	s_mov_b64 s[20:21], 0xea00000
	s_mov_b32 s51, 0x478bbced
	s_movk_i32 s52, 0x9f
	s_movk_i32 s53, 0x109
	v_add_u32_e32 v121, v2, v121
	v_lshlrev_b64 v[76:77], 1, v[76:77]
	s_mov_b32 s54, 0x4f3f
	v_readlane_b32 s100, v252, 4
	s_cmp_eq_u32 s100, 0x100
	s_cselect_b32 s54, s54, 0x8f3f
	v_mov_b32_e32 v123, 0xea00
	v_mov_b32_e32 v125, 5
	v_mov_b32_e32 v128, 0x23a40
	v_mov_b32_e32 v129, 0x23a38
	v_mov_b32_e32 v130, 6
	v_mov_b32_e32 v131, 0x80
	v_mov_b32_e32 v132, 0x23a20
	v_mov_b32_e32 v133, 0x23a18
	v_mov_b32_e32 v134, 0x23a10
	s_branch .LBB0_112

; __device__ __forceinline__ int opaque_tid() { int t = threadIdx.x; asm volatile("" : "+v"(t)); return t; }
;     for (int it = 0; it < budget; ++it) {
;         unsigned r = 0; if (lane == 0) r = __hip_atomic_fetch_add(ctr, 2u, __ATOMIC_RELAXED, __HIP_MEMORY_SCOPE_AGENT);
;         r = (unsigned)__builtin_amdgcn_readfirstlane((int)r) + (unsigned)CV_PRO_ITEMS;
;         if (r >= (unsigned)IT_LAYER) break;
;         cv_pair(a, lds, l, (int)r, wave, lane);
;     }
; }
; __global__ void __launch_bounds__(NTHREADS, 2) mk_fwd(Args args) {
;     ...
;             if (l + 1 < DEPTH && !(G >= 256 && bid < 128)) { __syncthreads(); const int tid_ = opaque_tid(); convert_layer_queue(pt, lds, l + 1, cvq, tid_ >> 6, tid_ & 63); }
.LBB0_560:
	v_readlane_b32 s0, v252, 4
	s_cmp_lg_u32 s0, 0x100
	s_cbranch_scc1 .LcvqA_ret
	v_readlane_b32 s0, v252, 0
	v_readlane_b32 s36, v255, 0
	s_cmp_lt_u32 s0, 64
	s_cbranch_scc1 .LcvqA_ret
	s_mov_b32 s64, s36
	v_readlane_b32 s0, v254, 53
	v_readlane_b32 s1, v254, 54
	s_mov_b32 s3, s1
	s_lshl_b32 s2, s36, 6
	s_lshl_b64 s[0:1], s[2:3], 2
	v_readlane_b32 s4, v254, 60
	v_readlane_b32 s5, v254, 61
	s_add_u32 s0, s4, s0
	s_addc_u32 s1, s5, s1
	s_add_u32 s0, s0, 0x8000
	s_addc_u32 s1, s1, 0
	s_add_i32 s2, s36, 0
	s_mul_hi_u32 s33, s2, 0x2c00000
	s_mul_i32 s34, s2, 0x2c00000
	s_mul_hi_u32 s35, s2, 0x1600000
	s_mul_i32 s50, s2, 0x1600000
	s_lshl_b32 s6, s2, 11
	s_mov_b32 s7, s3
	s_lshl_b64 s[8:9], s[2:3], 24
	s_lshl_b64 s[10:11], s[2:3], 23
	s_mul_hi_u32 s51, s2, 0xc00000
	s_mul_i32 s52, s2, 0xc00000
	s_mul_hi_u32 s53, s2, 0x7280000
	s_mul_i32 s54, s2, 0x7280000
	s_mul_hi_u32 s55, s2, 0x3a00000
	v_writelane_b32 v254, s2, 53
	v_mov_b32_e32 v2, v0
	s_mul_i32 s56, s2, 0x3a00000
	v_writelane_b32 v254, s3, 54
	s_waitcnt vmcnt(0) lgkmcnt(0)
	s_barrier
	s_movk_i32 s2, 0x4200
	v_lshrrev_b32_e32 v1, 6, v2
	v_and_b32_e32 v3, 63, v2
	v_readfirstlane_b32 s100, v1
	v_readlane_b32 s101, v252, 0
	s_sub_u32 s101, s101, 64
	s_lshl_b32 s101, s101, 3
	s_add_u32 s100, s100, s101
	s_lshl_b32 s100, s100, 1
	s_add_u32 s100, s100, 0x1000
	v_mul_lo_u32 v1, v1, s2
	v_cmp_eq_u32_e64 s[40:41], 0, v3
	v_add_u32_e32 v3, 0, v1
	v_lshlrev_b32_e32 v1, 2, v2
	v_and_b32_e32 v66, 28, v1
	v_bfe_u32 v1, v2, 3, 3
	v_lshlrev_b32_e32 v2, 3, v2
	v_and_b32_e32 v68, 56, v2
	v_lshl_add_u32 v4, v66, 2, v3
	v_mul_u32_u24_e32 v5, 0x84, v1
	v_mul_u32_u24_e32 v2, 0x84, v68
	v_lshlrev_b32_e32 v6, 2, v1
	v_or_b32_e32 v67, 8, v1
	v_or_b32_e32 v69, 16, v1
	v_or_b32_e32 v71, 24, v1
	v_or_b32_e32 v73, 32, v1
	v_or_b32_e32 v75, 40, v1
	v_or_b32_e32 v77, 48, v1
	v_or_b32_e32 v79, 56, v1
	v_add3_u32 v81, v3, v2, v6
	s_mov_b32 s57, 0x2
	v_add_u32_e32 v83, v4, v5
	s_branch .LcvqA_1381

;     __device__ __forceinline__ const float* in(int i) const { return (const float*)(const GAS float*)raw(i); }
;     __device__ __forceinline__ unsigned char* ws() const { return (unsigned char*)(GAS unsigned char*)raw(N_INPUTS + 1); }
; __device__ __forceinline__ CvItem cv_decode(const PT& a, int l, int r) {
;     unsigned char* ws = a.ws(); CvItem it;
;     if (r < IT_WIN) { const int kb = r / 458, nb = r % 458, n0 = nb * 32;
;         int drow; if (n0 < 2048) drow = n0; else if (n0 < 5120) drow = NIN_MAIN + (n0 - 2048); else if (n0 < 8512) drow = 2048 + (n0 - 5120); else drow = 5632 + (n0 - 8512);
;         it = CvItem{a.in(I_W_IN) + (size_t)l * D * NIN, NIN, kb * 64, n0, (bf16_t*)(ws + WS_WIN + l * WIN_L), D, drow, a.in(I_NORM_MIX_G) + l * D}; return it; }
;     r -= IT_WIN;
;     if (r < 3 * IT_BR) { const int br = r / IT_BR; r -= br * IT_BR; const int kb = r / 64, nb = r % 64;
;         it = CvItem{a.in(br == 0 ? I_W_BR_A : (br == 1 ? I_W_BR_B : I_W_BR_C)) + (size_t)l * 1024 * D, D, kb * 64, nb * 32, (bf16_t*)(ws + WS_WBR + l * WBR_L) + (size_t)br * D * 1024, 1024, nb * 32, nullptr}; return it; }
;     r -= 3 * IT_BR;
;     if (r < IT_OUT) { const int kb = r / 64, nb = r % 64;
;         it = CvItem{a.in(I_W_OUT) + (size_t)l * D * D, D, kb * 64, nb * 32, (bf16_t*)(ws + WS_WOUT + l * WOUT_L), D, nb * 32, nullptr}; return it; }
;     r -= IT_OUT;
;     if (r < 2 * IT_GU) { const int up = r / IT_GU; r -= up * IT_GU; const int kb = r / 176, nb = r % 176, n0 = nb * 32;
;         it = CvItem{a.in(up ? I_W_FFN_UP : I_W_FFN_GATE) + (size_t)l * D * DFF, DFF, kb * 64, n0, (bf16_t*)(ws + WS_WGU + l * WGU_L), D, 256 * (n0 / 128) + (n0 % 128) + 128 * up, a.in(I_NORM_FFN_G) + l * D}; return it; }
;     r -= 2 * IT_GU;
;     { const int kb = r / 64, nb = r % 64;
;       it = CvItem{a.in(I_W_FFN_DOWN) + (size_t)l * DFF * D, D, kb * 64, nb * 32, (bf16_t*)(ws + WS_WDN + l * WDN_L), DFF, nb * 32, nullptr}; }
;     for (int it = 0; it < budget; ++it) {
;         unsigned r = 0; if (lane == 0) r = __hip_atomic_fetch_add(ctr, 2u, __ATOMIC_RELAXED, __HIP_MEMORY_SCOPE_AGENT);
;         r = (unsigned)__builtin_amdgcn_readfirstlane((int)r) + (unsigned)CV_PRO_ITEMS;
;         if (r >= (unsigned)IT_LAYER) break;
;         cv_pair(a, lds, l, (int)r, wave, lane);
.LcvqA_1381:
	s_mov_b32 s24, s100
	s_add_u32 s100, s100, 0xc00
	s_add_i32 s24, s24, 0xffffc000
	s_cmp_lt_u32 s24, 0xffff70c0
	s_mov_b64 s[2:3], -1
	s_cbranch_scc1 .LcvqA_1380
	v_mov_b32_e32 v2, 0x23a60
	s_add_i32 s15, s24, 0x8f40
	v_add_u32_e32 v2, 0, v2
	ds_read_b64 v[2:3], v2
	s_cmpk_gt_u32 s15, 0x393f
	s_waitcnt lgkmcnt(0)
	v_readfirstlane_b32 s20, v3
	v_readfirstlane_b32 s21, v2
	s_cbranch_scc0 .LcvqA_1399
	s_cmpk_gt_u32 s15, 0x453f
	s_cbranch_scc0 .LcvqA_1396
	s_cmpk_gt_u32 s15, 0x4d3f
	s_mov_b64 s[18:19], -1
	s_cbranch_scc0 .LcvqA_1393
	s_cmpk_gt_u32 s15, 0x793f
	s_cbranch_scc0 .LcvqA_1391
	v_mov_b32_e32 v2, 0x23a48
	s_and_b32 s2, s15, 0x7fffffc0
	v_add_u32_e32 v2, 0, v2
	ds_read_b64 v[2:3], v2
	s_add_i32 s14, s2, 0xffff86c0
	s_waitcnt lgkmcnt(0)
	v_readfirstlane_b32 s3, v2
	v_readfirstlane_b32 s2, v3
	s_add_u32 s30, s3, s34
	s_addc_u32 s31, s2, s33
	s_lshl_b32 s2, s15, 5
	s_and_b32 s25, s2, 0x7e0
	s_add_u32 s2, s21, s50
	s_addc_u32 s3, s20, s35
	s_add_u32 s12, s2, 0x1ea00000
	s_addc_u32 s13, s3, 0
	s_mov_b64 s[2:3], 0

; __device__ __forceinline__ int opaque_tid() { int t = threadIdx.x; asm volatile("" : "+v"(t)); return t; }
;     for (int it = 0; it < budget; ++it) {
;         unsigned r = 0; if (lane == 0) r = __hip_atomic_fetch_add(ctr, 2u, __ATOMIC_RELAXED, __HIP_MEMORY_SCOPE_AGENT);
;         r = (unsigned)__builtin_amdgcn_readfirstlane((int)r) + (unsigned)CV_PRO_ITEMS;
;         if (r >= (unsigned)IT_LAYER) break;
;         cv_pair(a, lds, l, (int)r, wave, lane);
;     }
; }
; __global__ void __launch_bounds__(NTHREADS, 2) mk_fwd(Args args) {
;     ...
;             if (l + 1 < DEPTH && !(G >= 256 && bid < 128)) { __syncthreads(); const int tid_ = opaque_tid(); convert_layer_queue(pt, lds, l + 1, cvq, tid_ >> 6, tid_ & 63); }
.LBB0_1377:
	s_cmp_eq_u32 s64, 0x63
	v_readlane_b32 s2, v253, 61
	s_cselect_b64 s[0:1], -1, 0
	v_readlane_b32 s3, v253, 62
	s_or_b64 s[0:1], s[2:3], s[0:1]
	v_readlane_b32 s2, v252, 4
	s_cmp_lg_u32 s2, 0x100
	s_cselect_b64 s[2:3], -1, 0
	s_or_b64 s[0:1], s[0:1], s[2:3]
	v_readlane_b32 s28, v254, 55
	s_mov_b32 s36, s64
	s_and_b64 vcc, exec, s[0:1]
	v_readlane_b32 s29, v254, 56
	s_cbranch_vccnz .LBB0_1470
	v_readlane_b32 s0, v254, 53
	v_readlane_b32 s1, v254, 54
	s_mov_b32 s3, s1
	s_lshl_b32 s2, s36, 6
	s_lshl_b64 s[0:1], s[2:3], 2
	v_readlane_b32 s4, v254, 60
	v_readlane_b32 s5, v254, 61
	s_add_u32 s0, s4, s0
	s_addc_u32 s1, s5, s1
	s_add_u32 s0, s0, 0x8000
	s_addc_u32 s1, s1, 0
	s_add_i32 s2, s36, 0
	s_mul_hi_u32 s33, s2, 0x2c00000
	s_mul_i32 s34, s2, 0x2c00000
	s_mul_hi_u32 s35, s2, 0x1600000
	s_mul_i32 s50, s2, 0x1600000
	s_lshl_b32 s6, s2, 11
	s_mov_b32 s7, s3
	s_lshl_b64 s[8:9], s[2:3], 24
	s_lshl_b64 s[10:11], s[2:3], 23
	s_mul_hi_u32 s51, s2, 0xc00000
	s_mul_i32 s52, s2, 0xc00000
	s_mul_hi_u32 s53, s2, 0x7280000
	s_mul_i32 s54, s2, 0x7280000
	s_mul_hi_u32 s55, s2, 0x3a00000
	v_writelane_b32 v254, s2, 53
	v_mov_b32_e32 v2, v0
	s_mul_i32 s56, s2, 0x3a00000
	v_writelane_b32 v254, s3, 54
	s_waitcnt vmcnt(0) lgkmcnt(0)
	s_barrier
	s_movk_i32 s2, 0x4200
	v_lshrrev_b32_e32 v1, 6, v2
	v_and_b32_e32 v3, 63, v2
	v_readfirstlane_b32 s100, v1
	v_readlane_b32 s101, v252, 0
	s_sub_u32 s101, s101, 128
	s_lshl_b32 s101, s101, 3
	s_add_u32 s100, s100, s101
	s_lshl_b32 s100, s100, 1
	s_add_u32 s100, s100, 0x2800
	v_mul_lo_u32 v1, v1, s2
	v_cmp_eq_u32_e64 s[40:41], 0, v3
	v_add_u32_e32 v3, 0, v1
	v_lshlrev_b32_e32 v1, 2, v2
	v_and_b32_e32 v66, 28, v1
	v_bfe_u32 v1, v2, 3, 3
	v_lshlrev_b32_e32 v2, 3, v2
	v_and_b32_e32 v68, 56, v2
	v_lshl_add_u32 v4, v66, 2, v3
	v_mul_u32_u24_e32 v5, 0x84, v1
	v_mul_u32_u24_e32 v2, 0x84, v68
	v_lshlrev_b32_e32 v6, 2, v1
	v_or_b32_e32 v67, 8, v1
	v_or_b32_e32 v69, 16, v1
	v_or_b32_e32 v71, 24, v1
	v_or_b32_e32 v73, 32, v1
	v_or_b32_e32 v75, 40, v1
	v_or_b32_e32 v77, 48, v1
	v_or_b32_e32 v79, 56, v1
	v_add3_u32 v81, v3, v2, v6
	s_mov_b32 s57, 0x3
	v_add_u32_e32 v83, v4, v5
	s_branch .LBB0_1381

;     __device__ __forceinline__ const float* in(int i) const { return (const float*)(const GAS float*)raw(i); }
;     __device__ __forceinline__ unsigned char* ws() const { return (unsigned char*)(GAS unsigned char*)raw(N_INPUTS + 1); }
; __device__ __forceinline__ CvItem cv_decode(const PT& a, int l, int r) {
;     unsigned char* ws = a.ws(); CvItem it;
;     if (r < IT_WIN) { const int kb = r / 458, nb = r % 458, n0 = nb * 32;
;         int drow; if (n0 < 2048) drow = n0; else if (n0 < 5120) drow = NIN_MAIN + (n0 - 2048); else if (n0 < 8512) drow = 2048 + (n0 - 5120); else drow = 5632 + (n0 - 8512);
;         it = CvItem{a.in(I_W_IN) + (size_t)l * D * NIN, NIN, kb * 64, n0, (bf16_t*)(ws + WS_WIN + l * WIN_L), D, drow, a.in(I_NORM_MIX_G) + l * D}; return it; }
;     r -= IT_WIN;
;     if (r < 3 * IT_BR) { const int br = r / IT_BR; r -= br * IT_BR; const int kb = r / 64, nb = r % 64;
;         it = CvItem{a.in(br == 0 ? I_W_BR_A : (br == 1 ? I_W_BR_B : I_W_BR_C)) + (size_t)l * 1024 * D, D, kb * 64, nb * 32, (bf16_t*)(ws + WS_WBR + l * WBR_L) + (size_t)br * D * 1024, 1024, nb * 32, nullptr}; return it; }
;     r -= 3 * IT_BR;
;     if (r < IT_OUT) { const int kb = r / 64, nb = r % 64;
;         it = CvItem{a.in(I_W_OUT) + (size_t)l * D * D, D, kb * 64, nb * 32, (bf16_t*)(ws + WS_WOUT + l * WOUT_L), D, nb * 32, nullptr}; return it; }
;     r -= IT_OUT;
;     if (r < 2 * IT_GU) { const int up = r / IT_GU; r -= up * IT_GU; const int kb = r / 176, nb = r % 176, n0 = nb * 32;
;         it = CvItem{a.in(up ? I_W_FFN_UP : I_W_FFN_GATE) + (size_t)l * D * DFF, DFF, kb * 64, n0, (bf16_t*)(ws + WS_WGU + l * WGU_L), D, 256 * (n0 / 128) + (n0 % 128) + 128 * up, a.in(I_NORM_FFN_G) + l * D}; return it; }
;     r -= 2 * IT_GU;
;     { const int kb = r / 64, nb = r % 64;
;       it = CvItem{a.in(I_W_FFN_DOWN) + (size_t)l * DFF * D, D, kb * 64, nb * 32, (bf16_t*)(ws + WS_WDN + l * WDN_L), DFF, nb * 32, nullptr}; }
;     for (int it = 0; it < budget; ++it) {
;         unsigned r = 0; if (lane == 0) r = __hip_atomic_fetch_add(ctr, 2u, __ATOMIC_RELAXED, __HIP_MEMORY_SCOPE_AGENT);
;         r = (unsigned)__builtin_amdgcn_readfirstlane((int)r) + (unsigned)CV_PRO_ITEMS;
;         if (r >= (unsigned)IT_LAYER) break;
;         cv_pair(a, lds, l, (int)r, wave, lane);
.LBB0_1381:
	s_mov_b32 s24, s100
	s_add_u32 s100, s100, 0x800
	s_add_i32 s24, s24, 0xffffc000
	s_cmp_lt_u32 s24, 0xffff70c0
	s_mov_b64 s[2:3], -1
	s_cbranch_scc1 .LBB0_1380
	v_mov_b32_e32 v2, 0x23a60
	s_add_i32 s15, s24, 0x8f40
	v_add_u32_e32 v2, 0, v2
	ds_read_b64 v[2:3], v2
	s_cmpk_gt_u32 s15, 0x393f
	s_waitcnt lgkmcnt(0)
	v_readfirstlane_b32 s20, v3
	v_readfirstlane_b32 s21, v2
	s_cbranch_scc0 .LBB0_1399
	s_cmpk_gt_u32 s15, 0x453f
	s_cbranch_scc0 .LBB0_1396
	s_cmpk_gt_u32 s15, 0x4d3f
	s_mov_b64 s[18:19], -1
	s_cbranch_scc0 .LBB0_1393
	s_cmpk_gt_u32 s15, 0x793f
	s_cbranch_scc0 .LBB0_1391
	v_mov_b32_e32 v2, 0x23a48
	s_and_b32 s2, s15, 0x7fffffc0
	v_add_u32_e32 v2, 0, v2
	ds_read_b64 v[2:3], v2
	s_add_i32 s14, s2, 0xffff86c0
	s_waitcnt lgkmcnt(0)
	v_readfirstlane_b32 s3, v2
	v_readfirstlane_b32 s2, v3
	s_add_u32 s30, s3, s34
	s_addc_u32 s31, s2, s33
	s_lshl_b32 s2, s15, 5
	s_and_b32 s25, s2, 0x7e0
	s_add_u32 s2, s21, s50
	s_addc_u32 s3, s20, s35
	s_add_u32 s12, s2, 0x1ea00000
	s_addc_u32 s13, s3, 0
	s_mov_b64 s[2:3], 0

; __device__ __forceinline__ int opaque_tid() { int t = threadIdx.x; asm volatile("" : "+v"(t)); return t; }
;     for (int it = 0; it < budget; ++it) {
;         unsigned r = 0; if (lane == 0) r = __hip_atomic_fetch_add(ctr, 2u, __ATOMIC_RELAXED, __HIP_MEMORY_SCOPE_AGENT);
;         r = (unsigned)__builtin_amdgcn_readfirstlane((int)r) + (unsigned)CV_PRO_ITEMS;
;         if (r >= (unsigned)IT_LAYER) break;
;         cv_pair(a, lds, l, (int)r, wave, lane);
;     }
; }
; __global__ void __launch_bounds__(NTHREADS, 2) mk_fwd(Args args) {
;     ...
;             if (l + 1 < DEPTH && !(G >= 256 && bid < 128)) { __syncthreads(); const int tid_ = opaque_tid(); convert_layer_queue(pt, lds, l + 1, cvq, tid_ >> 6, tid_ & 63); }
.LBB0_1843:
	v_readlane_b32 s2, v252, 4
	s_cmp_lg_u32 s2, 0x100
	s_cbranch_scc1 .LcvqB_skip
	v_readlane_b32 s2, v252, 0
	s_cmp_lt_u32 s2, 128
	s_cbranch_scc1 .LcvqB_skip
	s_cmp_gt_u32 s36, 2
	s_cbranch_scc1 .LcvqB_skip
	v_writelane_b32 v255, s0, 8
	v_writelane_b32 v255, s1, 9
	v_writelane_b32 v255, s40, 10
	v_writelane_b32 v255, s41, 11
	s_mov_b32 s64, s36
	v_readlane_b32 s0, v254, 53
	v_readlane_b32 s1, v254, 54
	s_mov_b32 s3, s1
	s_lshl_b32 s2, s36, 6
	s_lshl_b64 s[0:1], s[2:3], 2
	v_readlane_b32 s4, v254, 60
	v_readlane_b32 s5, v254, 61
	s_add_u32 s0, s4, s0
	s_addc_u32 s1, s5, s1
	s_add_u32 s0, s0, 0x8000
	s_addc_u32 s1, s1, 0
	s_add_i32 s2, s36, 1
	s_mul_hi_u32 s33, s2, 0x2c00000
	s_mul_i32 s34, s2, 0x2c00000
	s_mul_hi_u32 s35, s2, 0x1600000
	s_mul_i32 s50, s2, 0x1600000
	s_lshl_b32 s6, s2, 11
	s_mov_b32 s7, s3
	s_lshl_b64 s[8:9], s[2:3], 24
	s_lshl_b64 s[10:11], s[2:3], 23
	s_mul_hi_u32 s51, s2, 0xc00000
	s_mul_i32 s52, s2, 0xc00000
	s_mul_hi_u32 s53, s2, 0x7280000
	s_mul_i32 s54, s2, 0x7280000
	s_mul_hi_u32 s55, s2, 0x3a00000
	v_writelane_b32 v254, s2, 53
	v_mov_b32_e32 v2, v0
	s_mul_i32 s56, s2, 0x3a00000
	v_writelane_b32 v254, s3, 54
	s_waitcnt vmcnt(0) lgkmcnt(0)
	s_barrier
	s_movk_i32 s2, 0x4200
	v_lshrrev_b32_e32 v1, 6, v2
	v_and_b32_e32 v3, 63, v2
	v_readfirstlane_b32 s100, v1
	v_readlane_b32 s101, v252, 0
	s_sub_u32 s101, s101, 128
	s_lshl_b32 s101, s101, 3
	s_add_u32 s100, s100, s101
	s_lshl_b32 s100, s100, 1
	s_add_u32 s100, s100, 0x0
	v_mul_lo_u32 v1, v1, s2
	v_cmp_eq_u32_e64 s[40:41], 0, v3
	v_add_u32_e32 v3, 0, v1
	v_lshlrev_b32_e32 v1, 2, v2
	v_and_b32_e32 v66, 28, v1
	v_bfe_u32 v1, v2, 3, 3
	v_lshlrev_b32_e32 v2, 3, v2
	v_and_b32_e32 v68, 56, v2
	v_lshl_add_u32 v4, v66, 2, v3
	v_mul_u32_u24_e32 v5, 0x84, v1
	v_mul_u32_u24_e32 v2, 0x84, v68
	v_lshlrev_b32_e32 v6, 2, v1
	v_or_b32_e32 v67, 8, v1
	v_or_b32_e32 v69, 16, v1
	v_or_b32_e32 v71, 24, v1
	v_or_b32_e32 v73, 32, v1
	v_or_b32_e32 v75, 40, v1
	v_or_b32_e32 v77, 48, v1
	v_or_b32_e32 v79, 56, v1
	v_add3_u32 v81, v3, v2, v6
	s_mov_b32 s57, 0x2
	v_add_u32_e32 v83, v4, v5
	s_branch .LcvqB_1381
